# P7 P.V steps: counted wait split (first MFMA waits for its two transposed reads only)
# baseline (speedup 1.0000x reference)
.LBB0_730:
	v_add_f32_e32 v1, v17, v174
	v_fmac_f32_e32 v1, v236, v16
	ds_read_b64_tr_b16 v[158:159], v2 offset:0x200
	ds_read_b64_tr_b16 v[160:161], v2 offset:0x1200
	ds_read_b64_tr_b16 v[162:163], v2 offset:0x2200
	ds_read_b64_tr_b16 v[164:165], v2 offset:0x3200
	s_waitcnt lgkmcnt(4)
	v_mfma_f32_32x32x16_bf16 v[114:129], v[150:153], v[8:11], v[114:129]
	v_mfma_f32_32x32x16_bf16 v[114:129], v[154:157], v[4:7], v[114:129]
	ds_read_b64_tr_b16 v[4:5], v2 offset:0x400
	ds_read_b64_tr_b16 v[6:7], v2 offset:0x1400
	ds_read_b64_tr_b16 v[8:9], v2 offset:0x2400
	ds_read_b64_tr_b16 v[10:11], v2 offset:0x3400
	s_waitcnt lgkmcnt(6)
	v_mfma_f32_32x32x16_bf16 v[82:97], v[150:153], v[158:161], v[82:97]
	s_waitcnt lgkmcnt(4)
	v_mfma_f32_32x32x16_bf16 v[82:97], v[154:157], v[162:165], v[82:97]
	ds_read_b64_tr_b16 v[158:159], v2 offset:0x600
	ds_read_b64_tr_b16 v[160:161], v2 offset:0x1600
	ds_read_b64_tr_b16 v[162:163], v2 offset:0x2600
	ds_read_b64_tr_b16 v[164:165], v2 offset:0x3600
	s_waitcnt lgkmcnt(6)
	v_mfma_f32_32x32x16_bf16 v[50:65], v[150:153], v[4:7], v[50:65]
	s_waitcnt lgkmcnt(4)
	v_mfma_f32_32x32x16_bf16 v[50:65], v[154:157], v[8:11], v[50:65]
	ds_read_b64_tr_b16 v[4:5], v2 offset:0x800
	ds_read_b64_tr_b16 v[6:7], v2 offset:0x1800
	ds_read_b64_tr_b16 v[8:9], v2 offset:0x2800
	ds_read_b64_tr_b16 v[10:11], v2 offset:0x3800
	s_waitcnt lgkmcnt(6)
	v_mfma_f32_32x32x16_bf16 v[18:33], v[150:153], v[158:161], v[18:33]
	s_waitcnt lgkmcnt(4)
	v_mfma_f32_32x32x16_bf16 v[18:33], v[154:157], v[162:165], v[18:33]
	ds_read_b64_tr_b16 v[158:159], v2 offset:0xa00
	ds_read_b64_tr_b16 v[160:161], v2 offset:0x1a00
	ds_read_b64_tr_b16 v[162:163], v2 offset:0x2a00
	ds_read_b64_tr_b16 v[164:165], v2 offset:0x3a00
	s_waitcnt lgkmcnt(6)
	v_mfma_f32_32x32x16_bf16 v[130:145], v[150:153], v[4:7], v[130:145]
	s_waitcnt lgkmcnt(4)
	v_mfma_f32_32x32x16_bf16 v[130:145], v[154:157], v[8:11], v[130:145]
	ds_read_b64_tr_b16 v[4:5], v2 offset:0xc00
	ds_read_b64_tr_b16 v[6:7], v2 offset:0x1c00
	ds_read_b64_tr_b16 v[8:9], v2 offset:0x2c00
	ds_read_b64_tr_b16 v[10:11], v2 offset:0x3c00
	s_waitcnt lgkmcnt(6)
	v_mfma_f32_32x32x16_bf16 v[98:113], v[150:153], v[158:161], v[98:113]
	s_waitcnt lgkmcnt(4)
	v_mfma_f32_32x32x16_bf16 v[98:113], v[154:157], v[162:165], v[98:113]
	ds_read_b64_tr_b16 v[158:159], v2 offset:0xe00
	ds_read_b64_tr_b16 v[160:161], v2 offset:0x1e00
	ds_read_b64_tr_b16 v[162:163], v2 offset:0x2e00
	ds_read_b64_tr_b16 v[164:165], v2 offset:0x3e00
	s_waitcnt lgkmcnt(6)
	v_mfma_f32_32x32x16_bf16 v[66:81], v[150:153], v[4:7], v[66:81]
	s_waitcnt lgkmcnt(4)
	v_mfma_f32_32x32x16_bf16 v[66:81], v[154:157], v[8:11], v[66:81]
	s_waitcnt lgkmcnt(2)
	v_mfma_f32_32x32x16_bf16 v[34:49], v[150:153], v[158:161], v[34:49]
	s_waitcnt lgkmcnt(0)
	v_mfma_f32_32x32x16_bf16 v[34:49], v[154:157], v[162:165], v[34:49]
	ds_read_b64_tr_b16 v[4:5], v2 offset:0x4000
	ds_read_b64_tr_b16 v[6:7], v2 offset:0x5000
	ds_read_b64_tr_b16 v[8:9], v2 offset:0x6000
	ds_read_b64_tr_b16 v[10:11], v2 offset:0x7000
	ds_read_b64_tr_b16 v[150:151], v2 offset:0x4200
	ds_read_b64_tr_b16 v[152:153], v2 offset:0x5200
	ds_read_b64_tr_b16 v[154:155], v2 offset:0x6200
	ds_read_b64_tr_b16 v[156:157], v2 offset:0x7200
	s_waitcnt lgkmcnt(4)
	s_nop 0
	v_mfma_f32_32x32x16_bf16 v[114:129], v[12:15], v[4:7], v[114:129]
	v_mfma_f32_32x32x16_bf16 v[114:129], v[146:149], v[8:11], v[114:129]
	ds_read_b64_tr_b16 v[4:5], v2 offset:0x4400
	ds_read_b64_tr_b16 v[6:7], v2 offset:0x5400
	ds_read_b64_tr_b16 v[8:9], v2 offset:0x6400
	ds_read_b64_tr_b16 v[10:11], v2 offset:0x7400
	s_waitcnt lgkmcnt(6)
	v_mfma_f32_32x32x16_bf16 v[82:97], v[12:15], v[150:153], v[82:97]
	s_waitcnt lgkmcnt(4)
	v_mfma_f32_32x32x16_bf16 v[82:97], v[146:149], v[154:157], v[82:97]
	ds_read_b64_tr_b16 v[150:151], v2 offset:0x4600
	ds_read_b64_tr_b16 v[152:153], v2 offset:0x5600
	ds_read_b64_tr_b16 v[154:155], v2 offset:0x6600
	ds_read_b64_tr_b16 v[156:157], v2 offset:0x7600
	s_waitcnt lgkmcnt(6)
	v_mfma_f32_32x32x16_bf16 v[50:65], v[12:15], v[4:7], v[50:65]
	s_waitcnt lgkmcnt(4)
	v_mfma_f32_32x32x16_bf16 v[50:65], v[146:149], v[8:11], v[50:65]
	ds_read_b64_tr_b16 v[4:5], v2 offset:0x4800
	ds_read_b64_tr_b16 v[6:7], v2 offset:0x5800
	ds_read_b64_tr_b16 v[8:9], v2 offset:0x6800
	ds_read_b64_tr_b16 v[10:11], v2 offset:0x7800
	s_waitcnt lgkmcnt(6)
	v_mfma_f32_32x32x16_bf16 v[18:33], v[12:15], v[150:153], v[18:33]
	s_waitcnt lgkmcnt(4)
	v_mfma_f32_32x32x16_bf16 v[18:33], v[146:149], v[154:157], v[18:33]
	ds_read_b64_tr_b16 v[150:151], v2 offset:0x4a00
	ds_read_b64_tr_b16 v[152:153], v2 offset:0x5a00
	ds_read_b64_tr_b16 v[154:155], v2 offset:0x6a00
	ds_read_b64_tr_b16 v[156:157], v2 offset:0x7a00
	s_waitcnt lgkmcnt(6)
	v_mfma_f32_32x32x16_bf16 v[130:145], v[12:15], v[4:7], v[130:145]
	s_waitcnt lgkmcnt(4)
	v_mfma_f32_32x32x16_bf16 v[130:145], v[146:149], v[8:11], v[130:145]
	ds_read_b64_tr_b16 v[4:5], v2 offset:0x4c00
	ds_read_b64_tr_b16 v[6:7], v2 offset:0x5c00
	ds_read_b64_tr_b16 v[8:9], v2 offset:0x6c00
	ds_read_b64_tr_b16 v[10:11], v2 offset:0x7c00
	s_waitcnt lgkmcnt(6)
	v_mfma_f32_32x32x16_bf16 v[98:113], v[12:15], v[150:153], v[98:113]
	s_waitcnt lgkmcnt(4)
	v_mfma_f32_32x32x16_bf16 v[98:113], v[146:149], v[154:157], v[98:113]
	ds_read_b64_tr_b16 v[150:151], v2 offset:0x4e00
	ds_read_b64_tr_b16 v[152:153], v2 offset:0x5e00
	ds_read_b64_tr_b16 v[154:155], v2 offset:0x6e00
	ds_read_b64_tr_b16 v[156:157], v2 offset:0x7e00
	s_waitcnt lgkmcnt(6)
	v_mfma_f32_32x32x16_bf16 v[66:81], v[12:15], v[4:7], v[66:81]
	s_waitcnt lgkmcnt(4)
	v_mfma_f32_32x32x16_bf16 v[66:81], v[146:149], v[8:11], v[66:81]
	s_waitcnt lgkmcnt(2)
	v_mfma_f32_32x32x16_bf16 v[34:49], v[12:15], v[150:153], v[34:49]
	s_waitcnt lgkmcnt(0)
	v_mfma_f32_32x32x16_bf16 v[34:49], v[146:149], v[154:157], v[34:49]
	v_mov_b32_e32 v236, v1
